# attention K/V staging: thread->(key,chunk) assignment changed so the V^T ds_write_b16 of a lane group no longer hit one LDS bank (rows 8 apart = 288 dwords = 0 mod 32 banks, 16-way conflict); same key
# speedup vs baseline: 1.0083x; 1.0063x over previous
.LBB0_880:
	s_or_b32 s22, s36, 0x180
	s_cmp_ge_i32 s46, s22
	v_cmp_eq_u32_e64 s[0:1], 0, v211
	v_lshrrev_b32_e32 v151, 8, v243
	v_lshlrev_b32_e32 v151, 4, v151
	v_and_or_b32 v151, v243, 15, v151
	v_lshlrev_b32_e32 v147, 2, v211
	s_cbranch_scc1 .LBB0_919
	s_add_u32 s4, s76, 0xb200000
	s_addc_u32 s5, s77, 0
	s_add_u32 s23, s76, 0xc600000
	s_addc_u32 s24, s77, 0
	s_add_u32 s25, s76, 0xcb00000
	s_addc_u32 s26, s77, 0
	v_bfe_u32 v1, v243, 4, 4
	s_add_u32 s27, s76, 0x110000
	v_lshl_add_u32 v2, v1, 4, 0
	s_movk_i32 s2, 0x470
	v_and_b32_e32 v146, 31, v243
	s_addc_u32 s28, s77, 0
	v_lshlrev_b32_e32 v150, 8, v151
	v_mad_u32_u24 v153, v1, s2, v2
	s_movk_i32 s2, 0x110
	v_lshlrev_b32_e32 v160, 1, v151
	s_add_u32 s29, s76, 0x150000
	v_mov_b32_e32 v149, 0
	v_lshlrev_b32_e32 v152, 3, v1
	v_add_u32_e32 v0, 0x2000, v150
	v_mad_u32_u24 v1, v146, s2, 0
	v_add_u32_e32 v3, 0, v144
	v_mul_u32_u24_e32 v4, 0x110, v151
	v_add_u32_e32 v5, 64, v160
	v_mul_u32_u24_e32 v6, 0x90, v146
	v_mad_i32_i24 v7, v211, -4, v146
	v_mbcnt_lo_u32_b32 v183, -1, 0
	s_addc_u32 s30, s77, 0
	s_mov_b32 s7, 0
	v_cndmask_b32_e64 v145, 0, 1.0, s[0:1]
	v_or_b32_e32 v161, 1, v147
	v_or_b32_e32 v162, 2, v147
	v_or_b32_e32 v163, 3, v147
	v_or_b32_e32 v164, 8, v147
	v_or_b32_e32 v165, 9, v147
	v_or_b32_e32 v166, 10, v147
	v_or_b32_e32 v167, 11, v147
	v_or_b32_e32 v168, 16, v147
	v_or_b32_e32 v169, 17, v147
	v_or_b32_e32 v170, 18, v147
	v_or_b32_e32 v171, 19, v147
	v_or_b32_e32 v172, 24, v147
	v_or_b32_e32 v173, 25, v147
	v_or_b32_e32 v174, 26, v147
	v_or_b32_e32 v175, 27, v147
	v_cmp_eq_u32_e64 s[2:3], 0, v243
	v_sub_u32_e32 v176, 0, v7
	v_subrev_u32_e32 v177, 27, v7
	v_lshlrev_b32_e32 v154, 1, v144
	v_mov_b32_e32 v155, v149
	v_mov_b32_e32 v178, 0x80
	v_lshlrev_b32_e32 v156, 1, v0
	v_add_u32_e32 v179, v2, v4
	v_add_u32_e32 v180, v153, v5
	v_add_u32_e32 v181, v1, v210
	s_movk_i32 s31, 0x81
	v_add_u32_e32 v182, v3, v6
	s_mov_b64 s[12:13], 0x14800800
	s_mov_b32 s33, 0x14800000
	s_add_i32 s35, 0, 0x24010
	v_mbcnt_hi_u32_b32 v184, -1, v183
	v_mov_b32_e32 v185, 0xf149f2ca
	s_branch .LBB0_884

.LBB0_919:
	s_or_b32 s23, s36, 0x280
	s_cmp_ge_i32 s46, s23
	s_cbranch_scc1 .LBB0_958
	s_add_u32 s4, s76, 0xb200000
	s_addc_u32 s5, s77, 0
	s_add_u32 s24, s76, 0xc600000
	s_addc_u32 s25, s77, 0
	s_add_u32 s26, s76, 0xcb00000
	s_addc_u32 s27, s77, 0
	v_bfe_u32 v1, v243, 4, 4
	s_add_u32 s28, s76, 0x110000
	v_lshl_add_u32 v2, v1, 4, 0
	s_movk_i32 s2, 0x470
	v_and_b32_e32 v146, 31, v243
	s_addc_u32 s29, s77, 0
	v_lshlrev_b32_e32 v148, 8, v151
	v_mad_u32_u24 v158, v1, s2, v2
	s_movk_i32 s2, 0x110
	v_mul_u32_u24_e32 v4, 0x110, v151
	v_lshlrev_b32_e32 v151, 1, v151
	s_add_u32 s30, s76, 0x150000
	v_mov_b32_e32 v145, 0
	v_cmp_eq_u32_e64 s[0:1], 0, v211
	v_lshlrev_b32_e32 v150, 3, v1
	v_add_u32_e32 v0, 0x2000, v148
	v_mad_u32_u24 v1, v146, s2, 0
	v_add_u32_e32 v3, 0, v144
	v_add_u32_e32 v5, 64, v151
	v_mul_u32_u24_e32 v6, 0x90, v146
	v_mad_i32_i24 v7, v211, -4, v146
	v_mbcnt_lo_u32_b32 v181, -1, 0
	s_addc_u32 s31, s77, 0
	s_mov_b32 s7, 0
	v_cndmask_b32_e64 v149, 0, 1.0, s[0:1]
	v_or_b32_e32 v159, 1, v147
	v_or_b32_e32 v160, 2, v147
	v_or_b32_e32 v161, 3, v147
	v_or_b32_e32 v162, 8, v147
	v_or_b32_e32 v163, 9, v147
	v_or_b32_e32 v164, 10, v147
	v_or_b32_e32 v165, 11, v147
	v_or_b32_e32 v166, 16, v147
	v_or_b32_e32 v167, 17, v147
	v_or_b32_e32 v168, 18, v147
	v_or_b32_e32 v169, 19, v147
	v_or_b32_e32 v170, 24, v147
	v_or_b32_e32 v171, 25, v147
	v_or_b32_e32 v172, 26, v147
	v_or_b32_e32 v173, 27, v147
	v_cmp_eq_u32_e64 s[2:3], 0, v243
	v_sub_u32_e32 v174, 0, v7
	v_subrev_u32_e32 v175, 27, v7
	v_lshlrev_b32_e32 v152, 1, v144
	v_mov_b32_e32 v153, v145
	v_mov_b32_e32 v176, 0x80
	v_lshlrev_b32_e32 v154, 1, v0
	v_add_u32_e32 v177, v2, v4
	v_add_u32_e32 v178, v158, v5
	v_add_u32_e32 v179, v1, v210
	s_movk_i32 s33, 0x81
	v_add_u32_e32 v180, v3, v6
	s_mov_b64 s[12:13], 0x14800800
	s_mov_b32 s34, 0x14800000
	s_add_i32 s35, 0, 0x24010
	v_mbcnt_hi_u32_b32 v182, -1, v181
	v_mov_b32_e32 v183, 0xf149f2ca
	s_branch .LBB0_923
